# phase 0 rebalanced: workgroups 0-95 (ada GEMV) no longer take a share of the cache-conversion and rope-table loops; on top of hand-pipelined phase_mid/phase_final and MLA LDS changes
# speedup vs baseline: 1.0385x; 1.0011x over previous
; DI void store_bf4(bf16_t* p, f32x4 v) { u32x2 w; w.x = pk2(v[0], v[1]); w.y = pk2(v[2], v[3]); *(u32x2*)p = w; }
; DI void phase0(KP P, char* lds) {
;     ...
;     const long gt = (long)bid * NTHREADS + tid, gn = (long)G * NTHREADS;
;     for (long i0 = gt; i0 < 8L * PAST * 64; i0 += 4 * gn) { f32x4 v[4];
; #pragma unroll
;         for (int r = 0; r < 4; ++r) { const long i = i0 + r * gn; if (i < 8L * PAST * 64) v[r] = *(const f32x4*)(P->c_ckv + i * 4); }
; #pragma unroll
;         for (int r = 0; r < 4; ++r) { const long i = i0 + r * gn; if (i < 8L * PAST * 64) { const long row = i >> 6; const int c = (int)(i & 63) * 4; const int bb = (int)(row >> 12), sq = (int)(row & 4095);
;             store_bf4(P->latent + (long)(MP + bb * SKEYS + sq) * 256 + c, v[r]); } } }
;     for (long i0 = gt; i0 < 8L * PAST * 8; i0 += 4 * gn) { f32x4 v[4];
; #pragma unroll
;         for (int r = 0; r < 4; ++r) { const long i = i0 + r * gn; if (i < 8L * PAST * 8) v[r] = *(const f32x4*)(P->c_kr + i * 4); }
; #pragma unroll
;         for (int r = 0; r < 4; ++r) { const long i = i0 + r * gn; if (i < 8L * PAST * 8) { const long row = i >> 3; const int c = (int)(i & 7) * 4; const int bb = (int)(row >> 12), sq = (int)(row & 4095);
;             store_bf4(P->krope + (long)(MP + bb * SKEYS + sq) * 32 + c, v[r]); } } }
;     for (long i = gt; i < 8L * 512 * 8; i += gn) { const long r = i >> 3; const int c = (int)(i & 7) * 4; const u32x2 z = {0u, 0u};
;         *(u32x2*)(P->vaT_s + r * SKP + SKEYS + c) = z; *(u32x2*)(P->vbT_s + r * SKP + SKEYS + c) = z; }
;     for (long i = gt; i < (long)TP * 16; i += gn) { const int pos = (int)(i >> 4), fi = (int)(i & 15);
;         const float inv = exp2f(-(float)fi * (13.287712379549449f / 16.0f));
;         const float ang = (float)pos * inv;
;         const double rev = (double)ang * 0.15915494309189535; const float fr_ = (float)(rev - floor(rev));
;         P->ropeT[i * 2] = __builtin_amdgcn_cosf(fr_); P->ropeT[i * 2 + 1] = __builtin_amdgcn_sinf(fr_); }
.LBB0_135:
	s_cmpk_lg_u32 s22, 0x100
	s_cbranch_scc1 .Lp0_keep
	s_cmpk_lt_u32 s26, 96
	s_cbranch_scc1 .LBB0_172
	s_sub_i32 s26, s26, 96
	s_movk_i32 s22, 0xa0
